# wconv tile loads issued together (one wait instead of eight); NSA selected-branch loop keeps two K/V blocks in flight with counted vmcnt
# speedup vs baseline: 1.0205x; 1.0205x over previous
; __device__ __forceinline__ unsigned cvt_pk_bf16(float lo, float hi) { f32x2 v = {lo, hi}; bf16x2_t b = __builtin_convertvector(v, bf16x2_t); return __builtin_bit_cast(unsigned, b); }
; #define LBAR() asm volatile("s_waitcnt lgkmcnt(0)\n\ts_barrier" ::: "memory")
; __device__ __forceinline__ void wconv_tile(LAS float* tl, const WDesc& d, bf16_t* Wb, int tile, const float* gain) {
;     ...
;   LBAR();
;   { const int kp = tid & 31;
; #pragma unroll
;     for (int rr = 0; rr < 4; ++rr) { const int nn = (tid >> 5) + 16 * rr; const unsigned wv = cvt_pk_bf16(tl[(2 * kp) * 65 + nn], tl[(2 * kp + 1) * 65 + nn]);
;       *(unsigned*)(Wb + d.dst + (size_t)(n0 + nn) * d.K + k0 + 2 * kp) = wv; } }
;   LBAR();
; }
; __device__ __forceinline__ void wconv_phase(LAS unsigned char* lds, const Ctx& X, int layer) {
;     ...
;   for (int t = X.blk; t < TOTAL; t += X.G) {
.Lwc_tail:
	v_ashrrev_i32_e32 v8, 5, v1
	v_lshlrev_b32_e32 v1, 1, v1
	v_and_b32_e32 v1, 62, v1
	v_mul_u32_u24_e32 v2, 0x104, v1
	v_lshlrev_b32_e32 v3, 2, v8
	s_waitcnt lgkmcnt(0)
	s_barrier
	v_add3_u32 v10, 0, v2, v3
	s_lshl_b64 s[8:9], s[70:71], 1
	ds_read2_b32 v[2:3], v10 offset1:16
	ds_read2_b32 v[4:5], v10 offset0:65 offset1:81
	s_add_u32 s10, s24, s8
	s_addc_u32 s11, s25, s9
	s_ashr_i32 s69, s68, 31
	s_lshl_b64 s[8:9], s[68:69], 1
	s_add_u32 s8, s10, s8
	v_add_u32_e32 v11, s35, v8
	s_addc_u32 s9, s11, s9
	v_lshlrev_b32_e32 v6, 1, v1
	v_mov_b32_e32 v7, v0
	s_waitcnt lgkmcnt(0)
	v_cvt_pk_bf16_f32 v1, v2, v4
	v_ashrrev_i32_e32 v2, 31, v11
	v_lshl_add_u64 v[6:7], s[8:9], 0, v[6:7]
	v_mul_lo_u32 v2, s64, v2
	v_mul_lo_u32 v4, s65, v11
	v_mad_u64_u32 v[8:9], s[8:9], s64, v11, 0
	v_add3_u32 v9, v9, v2, v4
	v_lshl_add_u64 v[8:9], v[8:9], 1, v[6:7]
	global_store_dword v[8:9], v1, off
	v_add_u32_e32 v8, 16, v11
	v_ashrrev_i32_e32 v2, 31, v8
	v_cvt_pk_bf16_f32 v1, v3, v5
	v_mul_lo_u32 v12, s64, v2
	ds_read2_b32 v[2:3], v10 offset0:32 offset1:48
	ds_read2_b32 v[4:5], v10 offset0:97 offset1:113
	v_mul_lo_u32 v13, s65, v8
	v_mad_u64_u32 v[8:9], s[8:9], s64, v8, 0
	v_add3_u32 v9, v9, v12, v13
	v_lshl_add_u64 v[8:9], v[8:9], 1, v[6:7]
	global_store_dword v[8:9], v1, off
	s_waitcnt lgkmcnt(0)
	v_cvt_pk_bf16_f32 v1, v2, v4
	v_add_u32_e32 v2, 32, v11
	v_ashrrev_i32_e32 v4, 31, v2
	v_mul_lo_u32 v4, s64, v4
	v_mul_lo_u32 v10, s65, v2
	v_mad_u64_u32 v[8:9], s[8:9], s64, v2, 0
	v_add3_u32 v9, v9, v4, v10
	v_lshl_add_u64 v[8:9], v[8:9], 1, v[6:7]
	v_add_u32_e32 v2, 48, v11
	global_store_dword v[8:9], v1, off
	v_cvt_pk_bf16_f32 v1, v3, v5
	v_ashrrev_i32_e32 v3, 31, v2
	v_mul_lo_u32 v4, s64, v3
	v_mul_lo_u32 v5, s65, v2
	v_mad_u64_u32 v[2:3], s[8:9], s64, v2, 0
	v_add3_u32 v3, v3, v4, v5
	v_lshl_add_u64 v[2:3], v[2:3], 1, v[6:7]
	global_store_dword v[2:3], v1, off
	s_waitcnt lgkmcnt(0)
	s_barrier
	s_add_i32 s34, s34, s30
	s_cmpk_lt_i32 s34, 0x134a
	s_mov_b64 s[78:79], 0x16060000
	s_cbranch_scc0 .LBB0_192

; __device__ __forceinline__ void wconv_tile(LAS float* tl, const WDesc& d, bf16_t* Wb, int tile, const float* gain) {
;     ...
;   { const int nn = tid & 63; const int sc = colmap(d.kind, n0 + nn, d.off);
; #pragma unroll
;     for (int rr = 0; rr < 8; ++rr) { const int kk = (tid >> 6) + 8 * rr; tl[kk * 65 + nn] = sc >= 0 ? d.src[(size_t)(k0 + kk) * d.pitch + sc] * (gain ? gain[k0 + kk] : 1.0f) : 0.f; } }
.LBB0_154:
	s_lshl_b32 s68, s40, 6
	s_waitcnt lgkmcnt(0)
	s_add_u32 s8, s10, s8
	s_addc_u32 s9, s11, s9
	v_mov_b32_e32 v5, v0
	s_cmp_lg_u64 s[78:79], 0
	v_cmp_lt_i32_e64 s[10:11], -1, v4
	v_lshl_add_u64 v[4:5], v[4:5], 2, s[8:9]
	s_cselect_b64 s[8:9], -1, 0
	v_cndmask_b32_e64 v6, 0, 1, s[8:9]
	v_ashrrev_i32_e32 v2, 6, v1
	v_mov_b32_e32 v7, 0
	v_cmp_ne_u32_e64 s[8:9], 1, v6
	s_movk_i32 s37, 0x104
	v_lshl_add_u32 v3, v3, 2, 0
	v_mul_lo_u32 v6, v2, s37
	v_add_u32_e32 v6, v3, v6
	v_mov_b32_e32 v60, 0
	v_mov_b32_e32 v61, 0
	v_mov_b32_e32 v62, 0
	v_mov_b32_e32 v63, 0
	v_mov_b32_e32 v64, 0
	v_mov_b32_e32 v65, 0
	v_mov_b32_e32 v66, 0
	v_mov_b32_e32 v67, 0
	v_mov_b32_e32 v68, 1.0
	v_mov_b32_e32 v69, 1.0
	v_mov_b32_e32 v70, 1.0
	v_mov_b32_e32 v71, 1.0
	v_mov_b32_e32 v72, 1.0
	v_mov_b32_e32 v73, 1.0
	v_mov_b32_e32 v74, 1.0
	v_mov_b32_e32 v75, 1.0
	s_and_saveexec_b64 s[44:45], s[10:11]
	s_cbranch_execz .Lwc_join
	v_add_u32_e32 v52, s68, v2
	v_mov_b32_e32 v57, 0
	v_mov_b32_e32 v59, 0
	v_mul_lo_u32 v56, v52, s76
	v_mov_b32_e32 v58, s76
	v_lshlrev_b32_e32 v58, 3, v58
	v_lshl_add_u64 v[8:9], v[56:57], 2, v[4:5]
	global_load_dword v60, v[8:9], off
	v_lshl_add_u64 v[8:9], v[58:59], 2, v[8:9]
	global_load_dword v61, v[8:9], off
	v_lshl_add_u64 v[8:9], v[58:59], 2, v[8:9]
	global_load_dword v62, v[8:9], off
	v_lshl_add_u64 v[8:9], v[58:59], 2, v[8:9]
	global_load_dword v63, v[8:9], off
	v_lshl_add_u64 v[8:9], v[58:59], 2, v[8:9]
	global_load_dword v64, v[8:9], off
	v_lshl_add_u64 v[8:9], v[58:59], 2, v[8:9]
	global_load_dword v65, v[8:9], off
	v_lshl_add_u64 v[8:9], v[58:59], 2, v[8:9]
	global_load_dword v66, v[8:9], off
	v_lshl_add_u64 v[8:9], v[58:59], 2, v[8:9]
	global_load_dword v67, v[8:9], off
	s_and_b64 vcc, exec, s[8:9]
	s_cbranch_vccnz .Lwc_nogain
	v_mov_b32_e32 v56, v52
	v_lshl_add_u64 v[10:11], v[56:57], 2, s[78:79]
	global_load_dword v68, v[10:11], off
	global_load_dword v69, v[10:11], off offset:32
	global_load_dword v70, v[10:11], off offset:64
	global_load_dword v71, v[10:11], off offset:96
	global_load_dword v72, v[10:11], off offset:128
	global_load_dword v73, v[10:11], off offset:160
	global_load_dword v74, v[10:11], off offset:192
	global_load_dword v75, v[10:11], off offset:224
.Lwc_nogain:
	s_waitcnt vmcnt(0)
	v_mul_f32_e32 v60, v60, v68
	v_mul_f32_e32 v61, v61, v69
	v_mul_f32_e32 v62, v62, v70
	v_mul_f32_e32 v63, v63, v71
	v_mul_f32_e32 v64, v64, v72
	v_mul_f32_e32 v65, v65, v73
	v_mul_f32_e32 v66, v66, v74
	v_mul_f32_e32 v67, v67, v75
.Lwc_join:
	s_or_b64 exec, exec, s[44:45]
	ds_write_b32 v6, v60
	ds_write_b32 v6, v61 offset:2080
	ds_write_b32 v6, v62 offset:4160
	ds_write_b32 v6, v63 offset:6240
	ds_write_b32 v6, v64 offset:8320
	ds_write_b32 v6, v65 offset:10400
	ds_write_b32 v6, v66 offset:12480
	ds_write_b32 v6, v67 offset:14560
	s_branch .Lwc_tail

; __device__ __forceinline__ void sel_load(SelFrag& F, const bf16_t* kst, const bf16_t* vst, int blk, int cq, int lg) {
;   const unsigned char* kp = (const unsigned char*)kst + (size_t)blk * 4096 + (cq * 4 + lg) * 16;
;   const unsigned char* vp = (const unsigned char*)vst + (size_t)blk * 4096 + (cq * 4 + lg) * 16;
; #pragma unroll
;   for (int t4 = 0; t4 < 4; ++t4) F.kf[t4] = *(const u32x4*)(kp + t4 * 1024);
; #pragma unroll
;   for (int dt = 0; dt < 4; ++dt) F.vf[dt] = *(const u32x4*)(vp + dt * 1024);
; }
; __device__ __forceinline__ int sel_slot(const u32x4& sl, int slot) {
;   const unsigned wsel = slot < 4 ? sl.x : slot < 8 ? sl.y : slot < 12 ? sl.z : sl.w;
;   return __builtin_amdgcn_readfirstlane((int)((wsel >> (8 * (slot & 3))) & 127u));
.LBB0_1347:
	s_cmp_lt_u32 s70, 12
	s_cselect_b32 s8, 2, 3
	s_cmp_gt_u32 s70, 7
	s_cselect_b32 s8, s8, 1
	s_cmp_gt_u32 s70, 3
	s_cselect_b32 s8, s8, 0
	s_cmp_eq_u32 s8, 1
	s_cselect_b64 vcc, -1, 0
	s_cmp_eq_u32 s8, 2
	v_cndmask_b32_e32 v34, v70, v71, vcc
	s_cselect_b64 vcc, -1, 0
	s_cmp_eq_u32 s8, 3
	v_cndmask_b32_e32 v34, v34, v72, vcc
	s_cselect_b64 vcc, -1, 0
	s_and_b32 s8, s68, 16
	v_cndmask_b32_e32 v34, v34, v73, vcc
	s_or_b32 s8, s8, 8
	v_lshrrev_b32_e32 v34, s8, v34
	s_nop 0
	v_readfirstlane_b32 s8, v34
	s_and_b32 s69, s8, 0x7f
	s_lshl_b32 s40, s69, 12
	v_lshl_add_u64 v[46:47], v[104:105], 0, s[40:41]
	v_lshl_add_u64 v[50:51], v[106:107], 0, s[40:41]
	global_load_dwordx4 v[34:37], v[46:47], off
	global_load_dwordx4 v[38:41], v[46:47], off offset:1024
	global_load_dwordx4 v[42:45], v[46:47], off offset:2048
	s_nop 0
	global_load_dwordx4 v[46:49], v[46:47], off offset:3072
	s_nop 0
	global_load_dwordx4 v[58:61], v[50:51], off
	global_load_dwordx4 v[62:65], v[50:51], off offset:1024
	global_load_dwordx4 v[66:69], v[50:51], off offset:2048
	s_nop 0
	global_load_dwordx4 v[50:53], v[50:51], off offset:3072
	s_waitcnt vmcnt(8)

; __device__ __forceinline__ float ex2(float x) { return __builtin_amdgcn_exp2f(x); }
; __device__ __forceinline__ long as_long(unsigned lo, unsigned hi) { return (long)(((unsigned long long)hi << 32) | (unsigned long long)lo); }
; __device__ __forceinline__ f32x4 mfma16_fp8(long a, long b, f32x4 c) { return __builtin_amdgcn_mfma_f32_16x16x32_fp8_fp8(a, b, c, 0, 0, 0); }
; __device__ __forceinline__ void sel_compute(const SelFrag& F, const long (&qs)[2], f32x4 (&os)[4], float& m, float& l, int blk, int cur, int t, int lg, float c) {
;   f32x4 s[4];
; #pragma unroll
;   for (int t4 = 0; t4 < 4; ++t4) { s[t4] = mfma16_fp8(as_long(F.kf[t4].x, F.kf[t4].y), qs[0], (f32x4){0.f, 0.f, 0.f, 0.f}); s[t4] = mfma16_fp8(as_long(F.kf[t4].z, F.kf[t4].w), qs[1], s[t4]); }
;   float mx = -INFINITY;
; #pragma unroll
;   for (int t4 = 0; t4 < 4; ++t4)
; #pragma unroll
;     for (int i = 0; i < 4; ++i) { if (blk == cur) { const int key = 64 * blk + 16 * t4 + 4 * lg + i; if (key > t) s[t4][i] = -INFINITY; } mx = fmaxf(mx, s[t4][i]); }
;   mx = max_x16_x32(mx);
;   if (__any(mx > m + 8.0f / c)) {
;     const float mnew = fmaxf(m, mx), ms2 = (mnew == -INFINITY) ? 0.f : mnew, alpha = ex2((m - ms2) * c);
;     m = mnew; l *= alpha;
; #pragma unroll
;     for (int dt = 0; dt < 4; ++dt) os[dt] *= alpha;
;   }
;   const float mcc = ((m == -INFINITY) ? 0.f : m) * c;
;   float p[4][4], ps = 0.f;
; #pragma unroll
;   for (int t4 = 0; t4 < 4; ++t4)
; #pragma unroll
;     for (int i = 0; i < 4; ++i) { p[t4][i] = ex2(s[t4][i] * c - mcc); ps += p[t4][i]; }
;   l += ps;
;   const u32x2 pa = pack8_fp8(p[0], p[1]), pb = pack8_fp8(p[2], p[3]);
;   const long pf0 = as_long(pa.x, pa.y), pf1 = as_long(pb.x, pb.y);
; #pragma unroll
;   for (int dt = 0; dt < 4; ++dt) { os[dt] = mfma16_fp8(as_long(F.vf[dt].x, F.vf[dt].y), pf0, os[dt]); os[dt] = mfma16_fp8(as_long(F.vf[dt].z, F.vf[dt].w), pf1, os[dt]); }
; }
.LBB0_1353:
	s_waitcnt vmcnt(15)
	v_mfma_f32_16x16x32_fp8_fp8 v[112:115], v[34:35], v[100:101], 0
	s_cmp_eq_u32 s69, s59
	v_lshl_or_b32 v138, s69, 6, v92
	s_cselect_b64 s[38:39], -1, 0
	v_mfma_f32_16x16x32_fp8_fp8 v[120:123], v[36:37], v[102:103], v[112:115]
	v_cmp_lt_i32_e32 vcc, s29, v138
	s_and_b64 vcc, s[38:39], vcc
	s_waitcnt vmcnt(14)
	v_mfma_f32_16x16x32_fp8_fp8 v[124:127], v[38:39], v[100:101], 0
	v_or_b32_e32 v112, 2, v138
	s_nop 2
	v_cndmask_b32_e32 v115, v120, v200, vcc
	v_cmp_le_i32_e32 vcc, s29, v138
	s_and_b64 vcc, s[38:39], vcc
	v_mfma_f32_16x16x32_fp8_fp8 v[126:129], v[40:41], v[102:103], v[124:127]
	v_cndmask_b32_e32 v118, v121, v200, vcc
	v_cmp_lt_i32_e32 vcc, s29, v112
	s_and_b64 vcc, s[38:39], vcc
	v_or_b32_e32 v112, 3, v138
	v_cndmask_b32_e32 v121, v122, v200, vcc
	v_cmp_lt_i32_e32 vcc, s29, v112
	s_and_b64 vcc, s[38:39], vcc
	v_or_b32_e32 v112, 16, v138
	v_cndmask_b32_e32 v123, v123, v200, vcc
	v_cmp_lt_i32_e32 vcc, s29, v112
	s_and_b64 vcc, s[38:39], vcc
	v_or_b32_e32 v112, 17, v138
	s_waitcnt vmcnt(13)
	v_mfma_f32_16x16x32_fp8_fp8 v[130:133], v[42:43], v[100:101], 0
	v_cndmask_b32_e32 v125, v126, v200, vcc
	v_cmp_lt_i32_e32 vcc, s29, v112
	s_and_b64 vcc, s[38:39], vcc
	v_or_b32_e32 v112, 18, v138
	v_cndmask_b32_e32 v126, v127, v200, vcc
	v_cmp_lt_i32_e32 vcc, s29, v112
	s_and_b64 vcc, s[38:39], vcc
	v_or_b32_e32 v112, 19, v138
	v_mfma_f32_16x16x32_fp8_fp8 v[130:133], v[44:45], v[102:103], v[130:133]
	v_cndmask_b32_e32 v124, v128, v200, vcc
	v_cmp_lt_i32_e32 vcc, s29, v112
	s_and_b64 vcc, s[38:39], vcc
	v_or_b32_e32 v112, 32, v138
	v_cndmask_b32_e32 v122, v129, v200, vcc
	v_cmp_lt_i32_e32 vcc, s29, v112
	s_and_b64 vcc, s[38:39], vcc
	v_or_b32_e32 v112, 33, v138
	s_waitcnt vmcnt(12)
	v_mfma_f32_16x16x32_fp8_fp8 v[134:137], v[46:47], v[100:101], 0
	v_cndmask_b32_e32 v120, v130, v200, vcc
	v_cmp_lt_i32_e32 vcc, s29, v112
	s_and_b64 vcc, s[38:39], vcc
	v_or_b32_e32 v112, 34, v138
	v_cndmask_b32_e32 v119, v131, v200, vcc
	v_cmp_lt_i32_e32 vcc, s29, v112
	s_and_b64 vcc, s[38:39], vcc
	v_or_b32_e32 v112, 35, v138
	v_mfma_f32_16x16x32_fp8_fp8 v[134:137], v[48:49], v[102:103], v[134:137]
	v_cndmask_b32_e32 v117, v132, v200, vcc
	v_cmp_lt_i32_e32 vcc, s29, v112
	v_max3_f32 v111, v115, s81, v118
	s_and_b64 vcc, s[38:39], vcc
	v_or_b32_e32 v112, 48, v138
	v_max3_f32 v111, v111, v121, v123
	v_cndmask_b32_e32 v116, v133, v200, vcc
	v_cmp_lt_i32_e32 vcc, s29, v112
	v_max3_f32 v111, v111, v125, v126
	s_and_b64 vcc, s[38:39], vcc
	v_or_b32_e32 v112, 49, v138
	v_max3_f32 v111, v111, v124, v122
	v_cndmask_b32_e32 v114, v134, v200, vcc
	v_cmp_lt_i32_e32 vcc, s29, v112
	v_max3_f32 v111, v111, v120, v119
	s_and_b64 vcc, s[38:39], vcc
	v_max3_f32 v111, v111, v117, v116
	v_cndmask_b32_e32 v113, v135, v200, vcc
	v_max3_f32 v127, v111, v114, v113
	v_or_b32_e32 v111, 50, v138
	v_cmp_lt_i32_e32 vcc, s29, v111
	s_and_b64 vcc, s[38:39], vcc
	v_or_b32_e32 v112, 51, v138
	v_cndmask_b32_e32 v111, v136, v200, vcc
	v_cmp_lt_i32_e32 vcc, s29, v112
	s_and_b64 vcc, s[38:39], vcc
	s_nop 0
	v_cndmask_b32_e32 v112, v137, v200, vcc
	v_max3_f32 v127, v127, v111, v112
	v_mov_b32_e32 v128, v127
	s_nop 1
	v_permlane16_swap_b32_e32 v127, v128
	v_max_f32_e32 v128, v128, v128
	v_max_f32_e32 v127, v127, v127
	v_max_f32_e32 v127, v127, v128
	v_mov_b32_e32 v128, v127
	s_nop 1
	v_permlane32_swap_b32_e32 v127, v128
	v_max_f32_e32 v128, v128, v128
	v_max_f32_e32 v127, v127, v127
	v_max_f32_e32 v127, v127, v128
	v_add_f32_e32 v128, 0x42317218, v109
	v_cmp_gt_f32_e32 vcc, v127, v128
	s_cbranch_vccz .LBB0_1355
	v_max_f32_e32 v110, v127, v127
	v_max_f32_e32 v127, v109, v109
	v_max_f32_e32 v127, v127, v110
	v_cmp_eq_f32_e32 vcc, s81, v127
	s_nop 1
	v_cndmask_b32_e64 v110, v127, 0, vcc
	v_sub_f32_e32 v109, v109, v110
	v_mul_f32_e32 v109, 0x3e38aa3b, v109
	v_exp_f32_e32 v110, v109
	v_mul_f32_e32 v109, 0x3e38aa3b, v127
	v_mul_f32_e32 v99, v99, v110
	v_pk_mul_f32 v[88:89], v[88:89], v[110:111] op_sel_hi:[1,0]
	v_pk_mul_f32 v[86:87], v[86:87], v[110:111] op_sel_hi:[1,0]
	v_pk_mul_f32 v[76:77], v[76:77], v[110:111] op_sel_hi:[1,0]
	v_pk_mul_f32 v[74:75], v[74:75], v[110:111] op_sel_hi:[1,0]
	v_pk_mul_f32 v[80:81], v[80:81], v[110:111] op_sel_hi:[1,0]
	v_pk_mul_f32 v[78:79], v[78:79], v[110:111] op_sel_hi:[1,0]
	v_pk_mul_f32 v[84:85], v[84:85], v[110:111] op_sel_hi:[1,0]
	v_pk_mul_f32 v[82:83], v[82:83], v[110:111] op_sel_hi:[1,0]
	v_cndmask_b32_e64 v110, v109, 0, vcc
	v_mov_b32_e32 v109, v127
.LBB0_1355:
	v_fma_f32 v115, v115, s42, -v110
	v_exp_f32_e32 v115, v115
	v_fma_f32 v118, v118, s42, -v110
	v_exp_f32_e32 v118, v118
	v_fma_f32 v121, v121, s42, -v110
	v_exp_f32_e32 v121, v121
	v_fma_f32 v123, v123, s42, -v110
	v_exp_f32_e32 v123, v123
	v_fma_f32 v125, v125, s42, -v110
	v_add_f32_e32 v127, 0, v115
	v_exp_f32_e32 v125, v125
	v_fma_f32 v126, v126, s42, -v110
	v_add_f32_e32 v127, v118, v127
	v_exp_f32_e32 v126, v126
	v_fma_f32 v124, v124, s42, -v110
	v_add_f32_e32 v127, v121, v127
	v_exp_f32_e32 v124, v124
	v_fma_f32 v122, v122, s42, -v110
	v_add_f32_e32 v127, v123, v127
	v_exp_f32_e32 v122, v122
	v_fma_f32 v120, v120, s42, -v110
	v_add_f32_e32 v127, v125, v127
	v_exp_f32_e32 v120, v120
	v_fma_f32 v119, v119, s42, -v110
	v_add_f32_e32 v127, v126, v127
	v_exp_f32_e32 v119, v119
	v_fma_f32 v117, v117, s42, -v110
	v_add_f32_e32 v127, v124, v127
	v_exp_f32_e32 v117, v117
	v_fma_f32 v116, v116, s42, -v110
	v_add_f32_e32 v127, v122, v127
	v_exp_f32_e32 v116, v116
	v_fma_f32 v114, v114, s42, -v110
	v_add_f32_e32 v127, v120, v127
	v_exp_f32_e32 v114, v114
	v_fma_f32 v113, v113, s42, -v110
	v_add_f32_e32 v127, v119, v127
	v_exp_f32_e32 v128, v113
	v_add_f32_e32 v127, v117, v127
	v_add_f32_e32 v127, v116, v127
	v_add_f32_e32 v127, v114, v127
	v_fma_f32 v111, v111, s42, -v110
	v_add_f32_e32 v113, v128, v127
	v_exp_f32_e32 v127, v111
	v_fma_f32 v110, v112, s42, -v110
	v_exp_f32_e32 v129, v110
	v_mov_b32_e32 v112, 0
	v_add_f32_e32 v111, v127, v113
	v_mov_b32_e32 v113, 0
	v_add_f32_e32 v110, v129, v111
	v_add_f32_e32 v99, v99, v110
	v_mov_b32_e32 v110, 0
	v_mov_b32_e32 v111, 0
	v_cvt_pk_fp8_f32 v110, v115, v118
	v_cvt_pk_fp8_f32 v111, v125, v126
	v_cvt_pk_fp8_f32 v112, v120, v119
	v_cvt_pk_fp8_f32 v113, v114, v128
	v_cvt_pk_fp8_f32 v110, v121, v123 op_sel:[0,0,1]
	v_cvt_pk_fp8_f32 v111, v124, v122 op_sel:[0,0,1]
	v_cvt_pk_fp8_f32 v112, v117, v116 op_sel:[0,0,1]
	v_cvt_pk_fp8_f32 v113, v127, v129 op_sel:[0,0,1]
	s_waitcnt vmcnt(11)
	v_mfma_f32_16x16x32_fp8_fp8 v[82:85], v[58:59], v[110:111], v[82:85]
	s_waitcnt vmcnt(10)
	v_mfma_f32_16x16x32_fp8_fp8 v[78:81], v[62:63], v[110:111], v[78:81]
	s_waitcnt vmcnt(9)
	v_mfma_f32_16x16x32_fp8_fp8 v[74:77], v[66:67], v[110:111], v[74:77]
	s_waitcnt vmcnt(8)
	v_mfma_f32_16x16x32_fp8_fp8 v[86:89], v[50:51], v[110:111], v[86:89]
	v_mfma_f32_16x16x32_fp8_fp8 v[82:85], v[60:61], v[112:113], v[82:85]
	v_mfma_f32_16x16x32_fp8_fp8 v[78:81], v[64:65], v[112:113], v[78:81]
	v_mfma_f32_16x16x32_fp8_fp8 v[74:77], v[68:69], v[112:113], v[74:77]
	v_mfma_f32_16x16x32_fp8_fp8 v[86:89], v[52:53], v[112:113], v[86:89]

; __device__ __forceinline__ void nsa_sel_phase(const Ctx& X, bf16_t* OBp) {
;     ...
;     for (int sidx = 0; sidx < nv; sidx += 2) {
;       const bool hasB = sidx + 1 < nv;
;       if (hasB) { blkB = sel_slot(sl, sidx + 1); sel_load(FB, projk, vst, blkB, cq, lg); }
;       sel_compute(FA, qs, os, m, l, blkA, cur, t, lg, c);
.Lsel_a0:
	s_waitcnt vmcnt(0)
	s_branch .LBB0_1348
